# static priority raise for waves 4-7 in the RG-LRU chunk loops
# baseline (speedup 1.0000x reference)
; __device__ __forceinline__ void chunk_info(int ci, int& seq, int& c) { if (ci < 130) { seq = ci / 65; c = ci - seq * 65; } else { const int t = ci - 130; const int q = t / 33; seq = 2 + q; c = t - q * 33; } }
; template <int MODE>
; __device__ __forceinline__ void lru_phase(const int TID, const int b, const int G, const Params& p, int l, LAS unsigned char* lds) {
;     ...
;     { int seq, c; chunk_info(it >> 3, seq, c); const int s0 = seq_start(seq), L = seq_len(seq), pos0 = (c == 0 ? -48 : 16 + 64 * (c - 1));
;       const bf16_t* xb = cols + (size_t)s0 * NINP + C_XC + gchc;
; #pragma unroll
;       for (int i = 0; i < 19; ++i) { const int pos = pos0 + rb * 16 - 2 + i; const int pc = pos < 0 ? 0 : (pos < L ? pos : L - 1); xr[i] = xb[(size_t)pc * NINP]; } }
.LBB0_363:
	v_ashrrev_i32_e32 v122, 3, v194
	v_and_b32_e32 v123, -16, v122
	v_subrev_u32_e32 v124, 50, v123
	s_add_u32 s92, s94, 0x12300000
	v_lshl_add_u32 v73, s2, 6, v124
	s_addc_u32 s93, s95, 0
	s_mul_i32 s3, s21, 0x5600
	v_min_u32_e32 v75, s0, v73
	s_mul_hi_i32 s1, s21, 0x5600
	s_add_u32 s8, s92, s3
	v_cmp_gt_i32_e32 vcc, 0, v73
	v_mul_u32_u24_e32 v75, 0x2b00, v75
	s_addc_u32 s9, s93, s1
	v_lshlrev_b32_e32 v182, 1, v70
	v_cndmask_b32_e64 v75, v75, 0, vcc
	v_lshl_add_u64 v[76:77], s[8:9], 0, v[182:183]
	v_lshlrev_b32_e32 v182, 1, v75
	v_or_b32_e32 v75, 1, v73
	v_min_u32_e32 v75, s0, v75
	s_mov_b64 s[8:9], 0x1400
	v_mul_u32_u24_e32 v75, 0x2b00, v75
	v_lshl_add_u64 v[76:77], v[76:77], 0, s[8:9]
	v_cndmask_b32_e64 v75, v75, 0, vcc
	v_lshl_add_u64 v[82:83], v[76:77], 0, v[182:183]
	v_lshlrev_b32_e32 v182, 1, v75
	v_add_u32_e32 v75, 2, v73
	v_min_u32_e32 v75, s0, v75
	v_mul_u32_u24_e32 v75, 0x2b00, v75
	v_cmp_lt_i32_e32 vcc, -3, v73
	flat_load_ushort v113, v[82:83]
	v_lshl_add_u64 v[82:83], v[76:77], 0, v[182:183]
	v_cndmask_b32_e32 v75, 0, v75, vcc
	v_lshlrev_b32_e32 v182, 1, v75
	v_add_u32_e32 v75, 3, v73
	v_min_u32_e32 v75, s0, v75
	v_mul_u32_u24_e32 v75, 0x2b00, v75
	v_cmp_lt_i32_e32 vcc, -4, v73
	flat_load_ushort v125, v[82:83]
	v_lshl_add_u64 v[82:83], v[76:77], 0, v[182:183]
	v_cndmask_b32_e32 v75, 0, v75, vcc
	v_lshlrev_b32_e32 v182, 1, v75
	v_add_u32_e32 v75, 4, v73
	v_min_u32_e32 v75, s0, v75
	v_mul_u32_u24_e32 v75, 0x2b00, v75
	v_cmp_lt_i32_e32 vcc, -5, v73
	flat_load_ushort v126, v[82:83]
	v_lshl_add_u64 v[82:83], v[76:77], 0, v[182:183]
	v_cndmask_b32_e32 v75, 0, v75, vcc
	v_lshlrev_b32_e32 v182, 1, v75
	v_add_u32_e32 v75, 5, v73
	v_min_u32_e32 v75, s0, v75
	v_mul_u32_u24_e32 v75, 0x2b00, v75
	v_cmp_lt_i32_e32 vcc, -6, v73
	flat_load_ushort v127, v[82:83]
	v_lshl_add_u64 v[82:83], v[76:77], 0, v[182:183]
	v_cndmask_b32_e32 v75, 0, v75, vcc
	v_lshlrev_b32_e32 v182, 1, v75
	v_add_u32_e32 v75, 6, v73
	v_min_u32_e32 v75, s0, v75
	v_mul_u32_u24_e32 v75, 0x2b00, v75
	v_cmp_lt_i32_e32 vcc, -7, v73
	flat_load_ushort v128, v[82:83]
	v_lshl_add_u64 v[82:83], v[76:77], 0, v[182:183]
	v_cndmask_b32_e32 v75, 0, v75, vcc
	v_lshlrev_b32_e32 v182, 1, v75
	v_add_u32_e32 v75, 7, v73
	v_min_u32_e32 v75, s0, v75
	v_mul_u32_u24_e32 v75, 0x2b00, v75
	v_cmp_lt_i32_e32 vcc, -8, v73
	flat_load_ushort v129, v[82:83]
	v_lshl_add_u64 v[82:83], v[76:77], 0, v[182:183]
	v_cndmask_b32_e32 v75, 0, v75, vcc
	v_lshlrev_b32_e32 v182, 1, v75
	v_add_u32_e32 v75, 8, v73
	v_min_u32_e32 v75, s0, v75
	v_mul_u32_u24_e32 v75, 0x2b00, v75
	v_cmp_lt_i32_e32 vcc, -9, v73
	flat_load_ushort v130, v[82:83]
	v_lshl_add_u64 v[82:83], v[76:77], 0, v[182:183]
	v_cndmask_b32_e32 v75, 0, v75, vcc
	v_lshlrev_b32_e32 v182, 1, v75
	v_add_u32_e32 v75, 9, v73
	v_min_u32_e32 v75, s0, v75
	v_mul_u32_u24_e32 v75, 0x2b00, v75
	v_cmp_lt_i32_e32 vcc, -10, v73
	flat_load_ushort v159, v[82:83]
	v_lshl_add_u64 v[82:83], v[76:77], 0, v[182:183]
	v_cndmask_b32_e32 v75, 0, v75, vcc
	v_lshlrev_b32_e32 v182, 1, v75
	v_add_u32_e32 v75, 10, v73
	v_min_u32_e32 v75, s0, v75
	v_mul_u32_u24_e32 v75, 0x2b00, v75
	v_cmp_lt_i32_e32 vcc, -11, v73
	flat_load_ushort v169, v[82:83]
	v_lshl_add_u64 v[82:83], v[76:77], 0, v[182:183]
	v_cndmask_b32_e32 v75, 0, v75, vcc
	v_lshlrev_b32_e32 v182, 1, v75
	v_add_u32_e32 v75, 11, v73
	v_min_u32_e32 v75, s0, v75
	v_mul_u32_u24_e32 v75, 0x2b00, v75
	v_cmp_lt_i32_e32 vcc, -12, v73
	flat_load_ushort v203, v[82:83]
	v_lshl_add_u64 v[82:83], v[76:77], 0, v[182:183]
	v_cndmask_b32_e32 v75, 0, v75, vcc
	v_lshlrev_b32_e32 v182, 1, v75
	v_add_u32_e32 v75, 12, v73
	v_min_u32_e32 v75, s0, v75
	v_mul_u32_u24_e32 v75, 0x2b00, v75
	v_cmp_lt_i32_e32 vcc, -13, v73
	flat_load_ushort v210, v[82:83]
	v_lshl_add_u64 v[82:83], v[76:77], 0, v[182:183]
	v_cndmask_b32_e32 v75, 0, v75, vcc
	v_lshlrev_b32_e32 v182, 1, v75
	v_add_u32_e32 v75, 13, v73
	v_min_u32_e32 v75, s0, v75
	v_mul_u32_u24_e32 v75, 0x2b00, v75
	v_cmp_lt_i32_e32 vcc, -14, v73
	flat_load_ushort v211, v[82:83]
	v_lshl_add_u64 v[82:83], v[76:77], 0, v[182:183]
	v_cndmask_b32_e32 v75, 0, v75, vcc
	v_lshlrev_b32_e32 v182, 1, v75
	v_add_u32_e32 v75, 14, v73
	v_min_u32_e32 v75, s0, v75
	v_mul_u32_u24_e32 v75, 0x2b00, v75
	v_cmp_lt_i32_e32 vcc, -15, v73
	flat_load_ushort v212, v[82:83]
	v_lshl_add_u64 v[82:83], v[76:77], 0, v[182:183]
	v_cndmask_b32_e32 v75, 0, v75, vcc
	v_lshlrev_b32_e32 v182, 1, v75
	v_add_u32_e32 v75, 15, v73
	v_min_u32_e32 v75, s0, v75
; __device__ __forceinline__ bf16_t f2bf(float f) { return (bf16_t)(cvt_pk_bf16(f, 0.f) & 0xffffu); }
; __device__ __forceinline__ float bf2f(bf16_t b) { return __uint_as_float(((unsigned)b) << 16); }
; __device__ __forceinline__ void chunk_info(int ci, int& seq, int& c) { if (ci < 130) { seq = ci / 65; c = ci - seq * 65; } else { const int t = ci - 130; const int q = t / 33; seq = 2 + q; c = t - q * 33; } }
; template <int MODE>
; __device__ __forceinline__ void lru_phase(const int TID, const int b, const int G, const Params& p, int l, LAS unsigned char* lds) {
;     ...
;     { int seq, c; chunk_info(it >> 3, seq, c); const int s0 = seq_start(seq), L = seq_len(seq), pos0 = (c == 0 ? -48 : 16 + 64 * (c - 1));
;       const bf16_t* xb = cols + (size_t)s0 * NINP + C_XC + gchc;
; #pragma unroll
;       for (int i = 0; i < 19; ++i) { const int pos = pos0 + rb * 16 - 2 + i; const int pc = pos < 0 ? 0 : (pos < L ? pos : L - 1); xr[i] = xb[(size_t)pc * NINP]; } }
;     for (; it < NCK * 8; it += G) {
;         const int ci = it >> 3;
;         int seq, c; chunk_info(ci, seq, c);
;         const int s0 = seq_start(seq);
;         const int pos0 = (c == 0 ? -48 : 16 + 64 * (c - 1));
;         const int rmin = (c == 0) ? 48 : 0;
;         float xv[19];
;         { const int L = seq_len(seq);
; #pragma unroll
;           for (int i = 0; i < 19; ++i) { const int pos = pos0 + rb * 16 - 2 + i; xv[i] = (pos >= 0 && pos < L) ? bf2f(xr[i]) : 0.f; } }
; #pragma unroll
;         for (int i = 0; i < 16; ++i) { const int r = rb * 16 + i; const float xc = (r >= rmin) ? cb + xv[i] * w0 + xv[i + 1] * w1 + xv[i + 2] * w2 + xv[i + 3] * w3 : 0.f;
;             xcf[r * 132 + ch] = xc; xcA[r * 136 + ch] = f2bf(xc); }
	v_mul_u32_u24_e32 v75, 0x2b00, v75
	v_cmp_lt_i32_e32 vcc, -16, v73
	flat_load_ushort v213, v[82:83]
	v_lshl_add_u64 v[82:83], v[76:77], 0, v[182:183]
	v_cndmask_b32_e32 v75, 0, v75, vcc
	v_lshlrev_b32_e32 v182, 1, v75
	v_add_u32_e32 v75, 16, v73
	v_min_u32_e32 v75, s0, v75
	s_movk_i32 s1, 0xffef
	v_mul_u32_u24_e32 v75, 0x2b00, v75
	v_cmp_lt_i32_e32 vcc, s1, v73
	flat_load_ushort v214, v[82:83]
	v_lshl_add_u64 v[82:83], v[76:77], 0, v[182:183]
	v_cndmask_b32_e32 v75, 0, v75, vcc
	v_lshlrev_b32_e32 v182, 1, v75
	v_add_u32_e32 v75, 17, v73
	v_min_u32_e32 v75, s0, v75
	s_movk_i32 s1, 0xffee
	v_mul_u32_u24_e32 v75, 0x2b00, v75
	v_cmp_lt_i32_e32 vcc, s1, v73
	flat_load_ushort v215, v[82:83]
	v_lshl_add_u64 v[82:83], v[76:77], 0, v[182:183]
	v_cndmask_b32_e32 v75, 0, v75, vcc
	v_lshlrev_b32_e32 v182, 1, v75
	v_add_u32_e32 v75, 18, v73
	v_min_u32_e32 v75, s0, v75
	s_movk_i32 s0, 0xffed
	v_mul_u32_u24_e32 v75, 0x2b00, v75
	v_cmp_lt_i32_e32 vcc, s0, v73
	flat_load_ushort v216, v[82:83]
	v_lshl_add_u64 v[82:83], v[76:77], 0, v[182:183]
	v_cndmask_b32_e32 v73, 0, v75, vcc
	v_lshlrev_b32_e32 v182, 1, v73
	v_lshl_add_u64 v[76:77], v[76:77], 0, v[182:183]
	flat_load_ushort v217, v[82:83]
	flat_load_ushort v218, v[76:77]
	v_lshlrev_b32_e32 v132, 2, v80
	v_lshlrev_b32_e32 v77, 2, v74
	v_readlane_b32 s0, v253, 47
	s_movk_i32 s1, 0x110
	v_add_u32_e32 v133, 0, v77
	v_add_u32_e32 v134, s0, v77
	v_lshl_add_u32 v77, v12, 1, 0
	v_mul_lo_u32 v81, v122, s1
	s_movk_i32 s0, 0x210
	v_or_b32_e32 v151, 15, v122
	v_or_b32_e32 v154, 1, v132
	v_mov_b32_e32 v85, 0x420
	v_mov_b32_e32 v86, 0x1ef0
	v_mov_b32_e32 v87, 0x2100
	v_mov_b32_e32 v88, 0x2310
	v_add_u32_e32 v135, v77, v81
	v_mul_lo_u32 v77, v123, s0
	v_mul_lo_u32 v82, v151, s0
	v_mul_f32_e32 v152, 0xc1000000, v78
	v_mad_u32_u24 v78, v154, s0, s0
	v_mad_u32_u24 v85, v154, s0, v85
	v_mad_u32_u24 v86, v154, s0, v86
	v_mad_u32_u24 v87, v154, s0, v87
	v_mad_u32_u24 v88, v154, s0, v88
	v_mad_u32_u24 v163, v154, s0, v231
	s_movk_i32 s0, 0x220
	v_mul_f32_e32 v168, 0xc1000000, v79
	v_mad_u32_u24 v79, v80, s0, v74
	s_movk_i32 s0, 0x88
	v_lshl_add_u32 v75, v71, 2, 0
	v_lshlrev_b32_e32 v71, 1, v71
	v_ashrrev_i32_e32 v73, 31, v72
	v_mad_u32_u24 v74, v154, s0, v74
	v_sub_u32_e32 v71, v75, v71
	v_lshl_add_u32 v76, v80, 4, 0
	v_mul_lo_u32 v81, v123, s1
	v_mul_lo_u32 v83, v151, s1
	v_mul_u32_u24_e32 v84, 0x110, v141
	v_lshl_add_u32 v171, v74, 1, 0
	v_lshl_add_u64 v[72:73], v[72:73], 2, s[94:95]
	s_mov_b64 s[0:1], 0x47f0d000
	v_add_u32_e32 v131, -2, v123
	v_or_b32_e32 v136, 1, v123
	v_or_b32_e32 v137, 2, v123
	v_or_b32_e32 v138, 3, v123
	v_or_b32_e32 v139, 4, v123
	v_or_b32_e32 v140, 5, v123
	v_or_b32_e32 v142, 6, v123
	v_or_b32_e32 v143, 7, v123
	v_or_b32_e32 v144, 8, v123
	v_or_b32_e32 v145, 9, v123
	v_or_b32_e32 v146, 10, v123
	v_or_b32_e32 v147, 11, v123
	v_or_b32_e32 v148, 12, v123
	v_or_b32_e32 v149, 13, v123
	v_or_b32_e32 v150, 14, v123
	v_mul_u32_u24_e32 v153, 0x840, v80
	v_mul_u32_u24_e32 v155, 0x210, v154
	v_or_b32_e32 v156, 2, v132
	v_or_b32_e32 v157, 3, v132
	v_or_b32_e32 v158, 16, v132
	v_or_b32_e32 v160, 17, v132
	v_or_b32_e32 v161, 18, v132
	v_or_b32_e32 v162, 19, v132
	v_or_b32_e32 v164, 32, v132
	v_or_b32_e32 v165, 33, v132
	v_or_b32_e32 v166, 34, v132
	v_or_b32_e32 v167, 35, v132
	v_cmp_eq_u32_e64 s[38:39], 0, v80
	v_cmp_eq_u32_e64 s[40:41], 1, v80
	v_cmp_eq_u32_e64 s[42:43], 2, v80
	v_cmp_eq_u32_e64 s[44:45], 3, v80
	v_lshl_add_u32 v170, v79, 1, 0
	v_add_u32_e32 v172, 0x110, v171
	v_add_u32_e32 v173, 0x220, v171
	v_add_u32_e32 v174, 0xff0, v171
	v_add_u32_e32 v175, 0x1100, v171
	v_add_u32_e32 v176, 0x1210, v171
	v_add_u32_e32 v177, 0x1320, v171
	v_add_u32_e32 v178, 0x20f0, v171
	v_add_u32_e32 v179, 0x2200, v171
	v_add_u32_e32 v180, 0x2310, v171
	v_add_u32_e32 v181, 0x2420, v171
	v_add_u32_e32 v195, 0x31f0, v171
	v_add_u32_e32 v196, 0x3300, v171
	v_add_u32_e32 v197, 0x3410, v171
	v_add_u32_e32 v198, 0x3520, v171
	v_lshl_add_u64 v[110:111], v[72:73], 0, s[0:1]
	v_add_u32_e32 v199, v75, v77
	v_add_u32_e32 v200, v71, v81
	v_add_u32_e32 v201, v75, v82
	v_add_u32_e32 v202, v71, v83
	v_lshlrev_b32_e32 v112, 1, v70
	v_add_u32_e32 v204, v76, v84
	v_add_u32_e32 v205, v133, v78
	v_add_u32_e32 v206, v133, v85
	v_add_u32_e32 v207, v133, v86
	v_add_u32_e32 v208, v133, v87
	v_add_u32_e32 v209, v133, v88
	s_mov_b32 s29, s22
	v_readfirstlane_b32 s98, v194
	s_cmpk_gt_u32 s98, 0xff
	s_cbranch_scc0 .Llru1_noprio
	s_setprio 1
.Llru1_noprio:
	s_branch .LBB0_365

; #define LBAR() do { asm volatile("s_waitcnt lgkmcnt(0)" ::: "memory"); __builtin_amdgcn_s_barrier(); asm volatile("" ::: "memory"); } while (0)
; template <int MODE>
; __device__ __forceinline__ void lru_phase(const int TID, const int b, const int G, const Params& p, int l, LAS unsigned char* lds) {
;     ...
;         LBAR();
;     }
; }
.LBB0_561:
	s_setprio 0
	s_mov_b64 s[0:1], 0

; __device__ __forceinline__ void chunk_info(int ci, int& seq, int& c) { if (ci < 130) { seq = ci / 65; c = ci - seq * 65; } else { const int t = ci - 130; const int q = t / 33; seq = 2 + q; c = t - q * 33; } }
; template <int MODE>
; __device__ __forceinline__ void lru_phase(const int TID, const int b, const int G, const Params& p, int l, LAS unsigned char* lds) {
;     ...
;     { int seq, c; chunk_info(it >> 3, seq, c); const int s0 = seq_start(seq), L = seq_len(seq), pos0 = (c == 0 ? -48 : 16 + 64 * (c - 1));
;       const bf16_t* xb = cols + (size_t)s0 * NINP + C_XC + gchc;
; #pragma unroll
;       for (int i = 0; i < 19; ++i) { const int pos = pos0 + rb * 16 - 2 + i; const int pc = pos < 0 ? 0 : (pos < L ? pos : L - 1); xr[i] = xb[(size_t)pc * NINP]; } }
.LBB0_816:
	v_and_b32_e32 v117, -16, v114
	v_subrev_u32_e32 v118, 50, v117
	s_add_u32 s21, s94, 0x12300000
	v_lshl_add_u32 v13, s2, 6, v118
	s_addc_u32 s23, s95, 0
	s_mul_i32 s3, s24, 0x5600
	v_min_u32_e32 v73, s0, v13
	s_mul_hi_i32 s1, s24, 0x5600
	s_add_u32 s28, s21, s3
	v_cmp_gt_i32_e32 vcc, 0, v13
	v_mul_u32_u24_e32 v73, 0x2b00, v73
	s_addc_u32 s29, s23, s1
	v_lshlrev_b32_e32 v182, 1, v70
	v_cndmask_b32_e64 v73, v73, 0, vcc
	v_lshl_add_u64 v[74:75], s[28:29], 0, v[182:183]
	v_lshlrev_b32_e32 v182, 1, v73
	v_or_b32_e32 v73, 1, v13
	v_min_u32_e32 v73, s0, v73
	s_mov_b64 s[8:9], 0x1400
	v_mul_u32_u24_e32 v73, 0x2b00, v73
	v_lshl_add_u64 v[74:75], v[74:75], 0, s[8:9]
	v_cndmask_b32_e64 v73, v73, 0, vcc
	v_lshl_add_u64 v[78:79], v[74:75], 0, v[182:183]
	v_lshlrev_b32_e32 v182, 1, v73
	v_add_u32_e32 v73, 2, v13
	v_min_u32_e32 v73, s0, v73
	v_mul_u32_u24_e32 v73, 0x2b00, v73
	v_cmp_lt_i32_e32 vcc, -3, v13
	flat_load_ushort v119, v[78:79]
	v_lshl_add_u64 v[78:79], v[74:75], 0, v[182:183]
	v_cndmask_b32_e32 v73, 0, v73, vcc
	v_lshlrev_b32_e32 v182, 1, v73
	v_add_u32_e32 v73, 3, v13
	v_min_u32_e32 v73, s0, v73
	v_mul_u32_u24_e32 v73, 0x2b00, v73
	v_cmp_lt_i32_e32 vcc, -4, v13
	flat_load_ushort v120, v[78:79]
	v_lshl_add_u64 v[78:79], v[74:75], 0, v[182:183]
	v_cndmask_b32_e32 v73, 0, v73, vcc
	v_lshlrev_b32_e32 v182, 1, v73
	v_add_u32_e32 v73, 4, v13
	v_min_u32_e32 v73, s0, v73
	v_mul_u32_u24_e32 v73, 0x2b00, v73
	v_cmp_lt_i32_e32 vcc, -5, v13
	flat_load_ushort v121, v[78:79]
	v_lshl_add_u64 v[78:79], v[74:75], 0, v[182:183]
	v_cndmask_b32_e32 v73, 0, v73, vcc
	v_lshlrev_b32_e32 v182, 1, v73
	v_add_u32_e32 v73, 5, v13
	v_min_u32_e32 v73, s0, v73
	v_mul_u32_u24_e32 v73, 0x2b00, v73
	v_cmp_lt_i32_e32 vcc, -6, v13
	flat_load_ushort v122, v[78:79]
	v_lshl_add_u64 v[78:79], v[74:75], 0, v[182:183]
	v_cndmask_b32_e32 v73, 0, v73, vcc
	v_lshlrev_b32_e32 v182, 1, v73
	v_add_u32_e32 v73, 6, v13
	v_min_u32_e32 v73, s0, v73
	v_mul_u32_u24_e32 v73, 0x2b00, v73
	v_cmp_lt_i32_e32 vcc, -7, v13
	flat_load_ushort v123, v[78:79]
	v_lshl_add_u64 v[78:79], v[74:75], 0, v[182:183]
	v_cndmask_b32_e32 v73, 0, v73, vcc
	v_lshlrev_b32_e32 v182, 1, v73
	v_add_u32_e32 v73, 7, v13
	v_min_u32_e32 v73, s0, v73
	v_mul_u32_u24_e32 v73, 0x2b00, v73
	v_cmp_lt_i32_e32 vcc, -8, v13
	flat_load_ushort v124, v[78:79]
	v_lshl_add_u64 v[78:79], v[74:75], 0, v[182:183]
	v_cndmask_b32_e32 v73, 0, v73, vcc
	v_lshlrev_b32_e32 v182, 1, v73
	v_add_u32_e32 v73, 8, v13
	v_min_u32_e32 v73, s0, v73
	v_mul_u32_u24_e32 v73, 0x2b00, v73
	v_cmp_lt_i32_e32 vcc, -9, v13
	flat_load_ushort v125, v[78:79]
	v_lshl_add_u64 v[78:79], v[74:75], 0, v[182:183]
	v_cndmask_b32_e32 v73, 0, v73, vcc
	v_lshlrev_b32_e32 v182, 1, v73
	v_add_u32_e32 v73, 9, v13
	v_min_u32_e32 v73, s0, v73
	v_mul_u32_u24_e32 v73, 0x2b00, v73
	v_cmp_lt_i32_e32 vcc, -10, v13
	flat_load_ushort v154, v[78:79]
	v_lshl_add_u64 v[78:79], v[74:75], 0, v[182:183]
	v_cndmask_b32_e32 v73, 0, v73, vcc
	v_lshlrev_b32_e32 v182, 1, v73
	v_add_u32_e32 v73, 10, v13
	v_min_u32_e32 v73, s0, v73
	v_mul_u32_u24_e32 v73, 0x2b00, v73
	v_cmp_lt_i32_e32 vcc, -11, v13
	flat_load_ushort v161, v[78:79]
	v_lshl_add_u64 v[78:79], v[74:75], 0, v[182:183]
	v_cndmask_b32_e32 v73, 0, v73, vcc
	v_lshlrev_b32_e32 v182, 1, v73
	v_add_u32_e32 v73, 11, v13
	v_min_u32_e32 v73, s0, v73
	v_mul_u32_u24_e32 v73, 0x2b00, v73
	v_cmp_lt_i32_e32 vcc, -12, v13
	flat_load_ushort v162, v[78:79]
	v_lshl_add_u64 v[78:79], v[74:75], 0, v[182:183]
	v_cndmask_b32_e32 v73, 0, v73, vcc
	v_lshlrev_b32_e32 v182, 1, v73
	v_add_u32_e32 v73, 12, v13
	v_min_u32_e32 v73, s0, v73
	v_mul_u32_u24_e32 v73, 0x2b00, v73
	v_cmp_lt_i32_e32 vcc, -13, v13
	flat_load_ushort v163, v[78:79]
; __device__ __forceinline__ bf16_t f2bf(float f) { return (bf16_t)(cvt_pk_bf16(f, 0.f) & 0xffffu); }
; __device__ __forceinline__ float bf2f(bf16_t b) { return __uint_as_float(((unsigned)b) << 16); }
; __device__ __forceinline__ void chunk_info(int ci, int& seq, int& c) { if (ci < 130) { seq = ci / 65; c = ci - seq * 65; } else { const int t = ci - 130; const int q = t / 33; seq = 2 + q; c = t - q * 33; } }
; template <int MODE>
; __device__ __forceinline__ void lru_phase(const int TID, const int b, const int G, const Params& p, int l, LAS unsigned char* lds) {
;     ...
;     { int seq, c; chunk_info(it >> 3, seq, c); const int s0 = seq_start(seq), L = seq_len(seq), pos0 = (c == 0 ? -48 : 16 + 64 * (c - 1));
;       const bf16_t* xb = cols + (size_t)s0 * NINP + C_XC + gchc;
; #pragma unroll
;       for (int i = 0; i < 19; ++i) { const int pos = pos0 + rb * 16 - 2 + i; const int pc = pos < 0 ? 0 : (pos < L ? pos : L - 1); xr[i] = xb[(size_t)pc * NINP]; } }
;     for (; it < NCK * 8; it += G) {
;         const int ci = it >> 3;
;         int seq, c; chunk_info(ci, seq, c);
;         const int s0 = seq_start(seq);
;         const int pos0 = (c == 0 ? -48 : 16 + 64 * (c - 1));
;         const int rmin = (c == 0) ? 48 : 0;
;         float xv[19];
;         { const int L = seq_len(seq);
; #pragma unroll
;           for (int i = 0; i < 19; ++i) { const int pos = pos0 + rb * 16 - 2 + i; xv[i] = (pos >= 0 && pos < L) ? bf2f(xr[i]) : 0.f; } }
; #pragma unroll
;         for (int i = 0; i < 16; ++i) { const int r = rb * 16 + i; const float xc = (r >= rmin) ? cb + xv[i] * w0 + xv[i + 1] * w1 + xv[i + 2] * w2 + xv[i + 3] * w3 : 0.f;
;             xcf[r * 132 + ch] = xc; xcA[r * 136 + ch] = f2bf(xc); }
	v_lshl_add_u64 v[78:79], v[74:75], 0, v[182:183]
	v_cndmask_b32_e32 v73, 0, v73, vcc
	v_lshlrev_b32_e32 v182, 1, v73
	v_add_u32_e32 v73, 13, v13
	v_min_u32_e32 v73, s0, v73
	v_mul_u32_u24_e32 v73, 0x2b00, v73
	v_cmp_lt_i32_e32 vcc, -14, v13
	flat_load_ushort v164, v[78:79]
	v_lshl_add_u64 v[78:79], v[74:75], 0, v[182:183]
	v_cndmask_b32_e32 v73, 0, v73, vcc
	v_lshlrev_b32_e32 v182, 1, v73
	v_add_u32_e32 v73, 14, v13
	v_min_u32_e32 v73, s0, v73
	v_mul_u32_u24_e32 v73, 0x2b00, v73
	v_cmp_lt_i32_e32 vcc, -15, v13
	flat_load_ushort v165, v[78:79]
	v_lshl_add_u64 v[78:79], v[74:75], 0, v[182:183]
	v_cndmask_b32_e32 v73, 0, v73, vcc
	v_lshlrev_b32_e32 v182, 1, v73
	v_add_u32_e32 v73, 15, v13
	v_min_u32_e32 v73, s0, v73
	v_mul_u32_u24_e32 v73, 0x2b00, v73
	v_cmp_lt_i32_e32 vcc, -16, v13
	flat_load_ushort v166, v[78:79]
	v_lshl_add_u64 v[78:79], v[74:75], 0, v[182:183]
	v_cndmask_b32_e32 v73, 0, v73, vcc
	v_lshlrev_b32_e32 v182, 1, v73
	v_add_u32_e32 v73, 16, v13
	v_min_u32_e32 v73, s0, v73
	s_movk_i32 s1, 0xffef
	v_mul_u32_u24_e32 v73, 0x2b00, v73
	v_cmp_lt_i32_e32 vcc, s1, v13
	flat_load_ushort v167, v[78:79]
	v_lshl_add_u64 v[78:79], v[74:75], 0, v[182:183]
	v_cndmask_b32_e32 v73, 0, v73, vcc
	v_lshlrev_b32_e32 v182, 1, v73
	v_add_u32_e32 v73, 17, v13
	v_min_u32_e32 v73, s0, v73
	s_movk_i32 s1, 0xffee
	v_mul_u32_u24_e32 v73, 0x2b00, v73
	v_cmp_lt_i32_e32 vcc, s1, v13
	flat_load_ushort v168, v[78:79]
	v_lshl_add_u64 v[78:79], v[74:75], 0, v[182:183]
	v_cndmask_b32_e32 v73, 0, v73, vcc
	v_lshlrev_b32_e32 v182, 1, v73
	v_add_u32_e32 v73, 18, v13
	v_min_u32_e32 v73, s0, v73
	s_movk_i32 s0, 0xffed
	v_mul_u32_u24_e32 v73, 0x2b00, v73
	v_cmp_lt_i32_e32 vcc, s0, v13
	flat_load_ushort v169, v[78:79]
	v_lshl_add_u64 v[78:79], v[74:75], 0, v[182:183]
	v_cndmask_b32_e32 v13, 0, v73, vcc
	v_lshlrev_b32_e32 v182, 1, v13
	v_lshl_add_u64 v[74:75], v[74:75], 0, v[182:183]
	flat_load_ushort v170, v[78:79]
	flat_load_ushort v171, v[74:75]
	v_lshlrev_b32_e32 v13, 1, v115
	v_lshlrev_b32_e32 v115, 2, v143
	s_add_u32 s2, s94, 0x478e5000
	s_movk_i32 s0, 0x210
	s_movk_i32 s1, 0x110
	v_or_b32_e32 v114, 15, v114
	v_or_b32_e32 v141, 1, v115
	s_addc_u32 s3, s95, 0
	v_sub_u32_e32 v73, v113, v13
	v_add_u32_e32 v74, 0, v134
	v_lshl_add_u32 v72, v72, 2, 0
	v_mul_lo_u32 v75, v117, s0
	v_mul_lo_u32 v77, v117, s1
	v_mul_lo_u32 v78, v114, s0
	v_mul_lo_u32 v79, v114, s1
	v_mul_u32_u24_e32 v80, 0x110, v142
	v_mul_f32_e32 v140, 0xc1000000, v71
	v_mul_u32_u24_e32 v71, 0x840, v143
	v_mul_u32_u24_e32 v81, 0x210, v141
	s_add_u32 s28, s94, 0x47bf9000
	v_ashrrev_i32_e32 v13, 31, v12
	v_cmp_eq_u32_e64 s[38:39], 0, v143
	v_or_b32_e32 v126, 1, v117
	v_or_b32_e32 v127, 2, v117
	v_or_b32_e32 v128, 3, v117
	v_or_b32_e32 v129, 4, v117
	v_or_b32_e32 v130, 5, v117
	v_or_b32_e32 v131, 6, v117
	v_or_b32_e32 v132, 7, v117
	v_or_b32_e32 v133, 8, v117
	v_or_b32_e32 v134, 9, v117
	v_or_b32_e32 v135, 10, v117
	v_or_b32_e32 v136, 11, v117
	v_or_b32_e32 v137, 12, v117
	v_or_b32_e32 v138, 13, v117
	v_or_b32_e32 v139, 14, v117
	v_or_b32_e32 v143, 2, v115
	v_or_b32_e32 v144, 3, v115
	v_or_b32_e32 v145, 16, v115
	v_or_b32_e32 v146, 17, v115
	v_or_b32_e32 v147, 18, v115
	v_or_b32_e32 v148, 19, v115
	v_or_b32_e32 v149, 32, v115
	v_or_b32_e32 v150, 33, v115
	v_or_b32_e32 v151, 34, v115
	v_or_b32_e32 v152, 35, v115
	v_mul_f32_e32 v153, 0xc1000000, v76
	s_addc_u32 s29, s95, 0
	v_add_u32_e32 v155, v113, v75
	v_add_u32_e32 v156, v73, v77
	v_add_u32_e32 v113, v113, v78
	v_add_u32_e32 v157, v73, v79
	v_lshlrev_b32_e32 v182, 1, v70
	v_add_u32_e32 v158, v74, v80
	v_add_u32_e32 v159, v72, v71
	v_add_u32_e32 v160, v72, v81
	s_mov_b32 s24, s22
	v_readfirstlane_b32 s98, v194
	s_cmpk_gt_u32 s98, 0xff
	s_cbranch_scc0 .Llru0_noprio
	s_setprio 1

; __device__ __forceinline__ bf16_t f2bf(float f) { return (bf16_t)(cvt_pk_bf16(f, 0.f) & 0xffffu); }
; __device__ __forceinline__ void s5_assemble_w(const int TID, const int BID, const Params& p, int l) {
;     ...
;     for (size_t idx = (size_t)BID * 512 + TID; idx < (size_t)32 * 256 * 512; idx += stride) {
;         const int g = (int)(idx >> 17), nout = (int)(idx >> 9) & 255, k = (int)idx & 511, t = nout >> 4, c = nout & 15;
;         float val;
;         if (k < 256) { const int s = k >> 4, cp = k & 15; val = 0.f;
;             const int jf = s <= t ? t - s : 0, jb = s >= t ? s - t : 0;
;             const float kf = kmat[((((size_t)g * 2 + 0) * 16 + jf) * 16 + c) * 16 + cp], kb = kmat[((((size_t)g * 2 + 1) * 16 + jb) * 16 + c) * 16 + cp], dsk = p.in[12][l * 512 + g * 16 + c];
;             val = (s <= t ? kf : 0.f) + (s >= t ? kb : 0.f) + ((s == t && c == cp) ? dsk : 0.f);
;         } else { const int kk = k - 256, d = kk >> 7, ri = (kk >> 6) & 1, n = kk & 63, j = d == 0 ? t + 1 : 16 - t;
;             const float cr = cre[(((size_t)(l * 2 + d) * 32 + g) * 16 + c) * 64 + n], ci = cim[(((size_t)(l * 2 + d) * 32 + g) * 16 + c) * 64 + n];
;             const f32x2 pv = pw[((size_t)(g * 2 + d) * 17 + j) * 64 + n];
;             val = ri == 0 ? cr * pv.x - ci * pv.y : -(cr * pv.y + ci * pv.x); }
;         wmat[idx] = f2bf(val);
.LBB0_1012:
	s_setprio 0
	s_cmpk_lg_i32 s96, 0x100
	s_cbranch_scc1 .Lsw_orig
	v_readlane_b32 s52, v254, 59
	v_lshrrev_b32_e32 v8, 8, v194
	v_and_b32_e32 v0, 63, v194
	v_lshlrev_b32_e32 v5, 1, v194
	v_readfirstlane_b32 s10, v8
	s_lshr_b32 s8, s22, 4
	s_and_b32 s9, s22, 15
	s_lshl_b32 s11, s22, 10
	s_add_u32 s54, s94, 0x48641000
	s_addc_u32 s55, s95, 0
	s_add_u32 s54, s54, s11
	s_addc_u32 s55, s55, 0
	s_cmp_lg_u32 s10, 0
	s_cbranch_scc1 .Lsw_pathb
	v_lshrrev_b32_e32 v1, 4, v194
	v_and_b32_e32 v2, 15, v194
	v_sub_u32_e32 v8, s8, v1
	v_max_i32_e32 v8, 0, v8
	v_subrev_u32_e32 v9, s8, v1
	v_max_i32_e32 v9, 0, v9
	s_lshl_b32 s11, s9, 4
	v_lshl_add_u32 v3, v8, 8, v2
	v_add_u32_e32 v3, s11, v3
	v_lshlrev_b32_e32 v3, 2, v3
	v_lshl_add_u32 v4, v9, 8, v2
	v_add_u32_e32 v4, s11, v4
	v_add_u32_e32 v4, 0x1000, v4
	v_lshlrev_b32_e32 v4, 2, v4
	v_cmp_ge_i32_e64 s[40:41], s8, v1
	v_cmp_le_i32_e64 s[42:43], s8, v1
	v_cmp_eq_u32_e64 s[44:45], s8, v1
	v_cmp_eq_u32_e64 s[46:47], s9, v2
	s_and_b64 s[44:45], s[44:45], s[46:47]
	s_add_u32 s48, s94, 0x4cec1000
	s_addc_u32 s49, s95, 0
	v_readlane_b32 s50, v254, 24
	v_readlane_b32 s51, v254, 25
	s_lshl_b32 s11, s52, 9
	s_add_i32 s11, s11, s9
	s_lshl_b32 s11, s11, 2
	s_add_u32 s50, s50, s11
	s_addc_u32 s51, s51, 0
	global_load_dword v32, v3, s[48:49]
	global_load_dword v48, v4, s[48:49]
	global_load_dword v64, v183, s[50:51] offset:0
	s_add_u32 s48, s48, 0x8000
	s_addc_u32 s49, s49, 0
	global_load_dword v33, v3, s[48:49]
	global_load_dword v49, v4, s[48:49]
	global_load_dword v65, v183, s[50:51] offset:64
	s_add_u32 s48, s48, 0x8000
	s_addc_u32 s49, s49, 0
	global_load_dword v34, v3, s[48:49]
	global_load_dword v50, v4, s[48:49]
	global_load_dword v66, v183, s[50:51] offset:128
	s_add_u32 s48, s48, 0x8000
	s_addc_u32 s49, s49, 0
	global_load_dword v35, v3, s[48:49]
	global_load_dword v51, v4, s[48:49]
	global_load_dword v67, v183, s[50:51] offset:192
	s_add_u32 s48, s48, 0x8000
	s_addc_u32 s49, s49, 0
	global_load_dword v36, v3, s[48:49]
	global_load_dword v52, v4, s[48:49]
	global_load_dword v68, v183, s[50:51] offset:256
	s_add_u32 s48, s48, 0x8000
	s_addc_u32 s49, s49, 0
	global_load_dword v37, v3, s[48:49]
	global_load_dword v53, v4, s[48:49]
	global_load_dword v69, v183, s[50:51] offset:320
	s_add_u32 s48, s48, 0x8000
	s_addc_u32 s49, s49, 0
	global_load_dword v38, v3, s[48:49]
	global_load_dword v54, v4, s[48:49]
	global_load_dword v70, v183, s[50:51] offset:384
	s_add_u32 s48, s48, 0x8000
	s_addc_u32 s49, s49, 0
	global_load_dword v39, v3, s[48:49]
	global_load_dword v55, v4, s[48:49]
	global_load_dword v71, v183, s[50:51] offset:448
	s_add_u32 s48, s48, 0x8000
	s_addc_u32 s49, s49, 0
	global_load_dword v40, v3, s[48:49]
	global_load_dword v56, v4, s[48:49]
	global_load_dword v72, v183, s[50:51] offset:512
	s_add_u32 s48, s48, 0x8000
	s_addc_u32 s49, s49, 0
	global_load_dword v41, v3, s[48:49]
	global_load_dword v57, v4, s[48:49]
	global_load_dword v73, v183, s[50:51] offset:576
	s_add_u32 s48, s48, 0x8000
	s_addc_u32 s49, s49, 0
	global_load_dword v42, v3, s[48:49]
	global_load_dword v58, v4, s[48:49]
	global_load_dword v74, v183, s[50:51] offset:640
	s_add_u32 s48, s48, 0x8000
	s_addc_u32 s49, s49, 0
	global_load_dword v43, v3, s[48:49]
	global_load_dword v59, v4, s[48:49]
	global_load_dword v75, v183, s[50:51] offset:704
	s_add_u32 s48, s48, 0x8000
	s_addc_u32 s49, s49, 0
	global_load_dword v44, v3, s[48:49]
	global_load_dword v60, v4, s[48:49]
	global_load_dword v76, v183, s[50:51] offset:768
	s_add_u32 s48, s48, 0x8000
	s_addc_u32 s49, s49, 0
	global_load_dword v45, v3, s[48:49]
	global_load_dword v61, v4, s[48:49]
	global_load_dword v77, v183, s[50:51] offset:832
	s_add_u32 s48, s48, 0x8000
	s_addc_u32 s49, s49, 0
	global_load_dword v46, v3, s[48:49]
	global_load_dword v62, v4, s[48:49]
	global_load_dword v78, v183, s[50:51] offset:896
	s_add_u32 s48, s48, 0x8000
	s_addc_u32 s49, s49, 0
	global_load_dword v47, v3, s[48:49]
	global_load_dword v63, v4, s[48:49]
	global_load_dword v79, v183, s[50:51] offset:960
	s_add_u32 s48, s48, 0x8000
	s_addc_u32 s49, s49, 0
	s_waitcnt vmcnt(0)
	v_cndmask_b32_e64 v32, 0, v32, s[40:41]
	v_cndmask_b32_e64 v48, 0, v48, s[42:43]
	v_cndmask_b32_e64 v64, 0, v64, s[44:45]
	v_add_f32_e32 v32, v32, v48
	v_add_f32_e32 v32, v32, v64
	v_cvt_pk_bf16_f32 v32, v32, v183
	global_store_short v5, v32, s[54:55]
	s_add_u32 s54, s54, 0x40000
	s_addc_u32 s55, s55, 0
	v_cndmask_b32_e64 v33, 0, v33, s[40:41]
	v_cndmask_b32_e64 v49, 0, v49, s[42:43]
	v_cndmask_b32_e64 v65, 0, v65, s[44:45]
	v_add_f32_e32 v33, v33, v49
	v_add_f32_e32 v33, v33, v65
	v_cvt_pk_bf16_f32 v33, v33, v183
	global_store_short v5, v33, s[54:55]
	s_add_u32 s54, s54, 0x40000
	s_addc_u32 s55, s55, 0
	v_cndmask_b32_e64 v34, 0, v34, s[40:41]
	v_cndmask_b32_e64 v50, 0, v50, s[42:43]
	v_cndmask_b32_e64 v66, 0, v66, s[44:45]
	v_add_f32_e32 v34, v34, v50
	v_add_f32_e32 v34, v34, v66
	v_cvt_pk_bf16_f32 v34, v34, v183
	global_store_short v5, v34, s[54:55]
	s_add_u32 s54, s54, 0x40000
	s_addc_u32 s55, s55, 0
	v_cndmask_b32_e64 v35, 0, v35, s[40:41]
	v_cndmask_b32_e64 v51, 0, v51, s[42:43]
	v_cndmask_b32_e64 v67, 0, v67, s[44:45]
	v_add_f32_e32 v35, v35, v51
	v_add_f32_e32 v35, v35, v67
	v_cvt_pk_bf16_f32 v35, v35, v183
	global_store_short v5, v35, s[54:55]
	s_add_u32 s54, s54, 0x40000
	s_addc_u32 s55, s55, 0
	v_cndmask_b32_e64 v36, 0, v36, s[40:41]
	v_cndmask_b32_e64 v52, 0, v52, s[42:43]
	v_cndmask_b32_e64 v68, 0, v68, s[44:45]
	v_add_f32_e32 v36, v36, v52
	v_add_f32_e32 v36, v36, v68
	v_cvt_pk_bf16_f32 v36, v36, v183
	global_store_short v5, v36, s[54:55]
	s_add_u32 s54, s54, 0x40000
	s_addc_u32 s55, s55, 0
	v_cndmask_b32_e64 v37, 0, v37, s[40:41]
; __device__ __forceinline__ bf16_t f2bf(float f) { return (bf16_t)(cvt_pk_bf16(f, 0.f) & 0xffffu); }
; __device__ __forceinline__ void s5_assemble_w(const int TID, const int BID, const Params& p, int l) {
;     ...
;         if (k < 256) { const int s = k >> 4, cp = k & 15; val = 0.f;
;             const int jf = s <= t ? t - s : 0, jb = s >= t ? s - t : 0;
;             const float kf = kmat[((((size_t)g * 2 + 0) * 16 + jf) * 16 + c) * 16 + cp], kb = kmat[((((size_t)g * 2 + 1) * 16 + jb) * 16 + c) * 16 + cp], dsk = p.in[12][l * 512 + g * 16 + c];
;             val = (s <= t ? kf : 0.f) + (s >= t ? kb : 0.f) + ((s == t && c == cp) ? dsk : 0.f);
;         } else { const int kk = k - 256, d = kk >> 7, ri = (kk >> 6) & 1, n = kk & 63, j = d == 0 ? t + 1 : 16 - t;
;             const float cr = cre[(((size_t)(l * 2 + d) * 32 + g) * 16 + c) * 64 + n], ci = cim[(((size_t)(l * 2 + d) * 32 + g) * 16 + c) * 64 + n];
;             const f32x2 pv = pw[((size_t)(g * 2 + d) * 17 + j) * 64 + n];
;             val = ri == 0 ? cr * pv.x - ci * pv.y : -(cr * pv.y + ci * pv.x); }
;         wmat[idx] = f2bf(val);
	v_cndmask_b32_e64 v53, 0, v53, s[42:43]
	v_cndmask_b32_e64 v69, 0, v69, s[44:45]
	v_add_f32_e32 v37, v37, v53
	v_add_f32_e32 v37, v37, v69
	v_cvt_pk_bf16_f32 v37, v37, v183
	global_store_short v5, v37, s[54:55]
	s_add_u32 s54, s54, 0x40000
	s_addc_u32 s55, s55, 0
	v_cndmask_b32_e64 v38, 0, v38, s[40:41]
	v_cndmask_b32_e64 v54, 0, v54, s[42:43]
	v_cndmask_b32_e64 v70, 0, v70, s[44:45]
	v_add_f32_e32 v38, v38, v54
	v_add_f32_e32 v38, v38, v70
	v_cvt_pk_bf16_f32 v38, v38, v183
	global_store_short v5, v38, s[54:55]
	s_add_u32 s54, s54, 0x40000
	s_addc_u32 s55, s55, 0
	v_cndmask_b32_e64 v39, 0, v39, s[40:41]
	v_cndmask_b32_e64 v55, 0, v55, s[42:43]
	v_cndmask_b32_e64 v71, 0, v71, s[44:45]
	v_add_f32_e32 v39, v39, v55
	v_add_f32_e32 v39, v39, v71
	v_cvt_pk_bf16_f32 v39, v39, v183
	global_store_short v5, v39, s[54:55]
	s_add_u32 s54, s54, 0x40000
	s_addc_u32 s55, s55, 0
	v_cndmask_b32_e64 v40, 0, v40, s[40:41]
	v_cndmask_b32_e64 v56, 0, v56, s[42:43]
	v_cndmask_b32_e64 v72, 0, v72, s[44:45]
	v_add_f32_e32 v40, v40, v56
	v_add_f32_e32 v40, v40, v72
	v_cvt_pk_bf16_f32 v40, v40, v183
	global_store_short v5, v40, s[54:55]
	s_add_u32 s54, s54, 0x40000
	s_addc_u32 s55, s55, 0
	v_cndmask_b32_e64 v41, 0, v41, s[40:41]
	v_cndmask_b32_e64 v57, 0, v57, s[42:43]
	v_cndmask_b32_e64 v73, 0, v73, s[44:45]
	v_add_f32_e32 v41, v41, v57
	v_add_f32_e32 v41, v41, v73
	v_cvt_pk_bf16_f32 v41, v41, v183
	global_store_short v5, v41, s[54:55]
	s_add_u32 s54, s54, 0x40000
	s_addc_u32 s55, s55, 0
	v_cndmask_b32_e64 v42, 0, v42, s[40:41]
	v_cndmask_b32_e64 v58, 0, v58, s[42:43]
	v_cndmask_b32_e64 v74, 0, v74, s[44:45]
	v_add_f32_e32 v42, v42, v58
	v_add_f32_e32 v42, v42, v74
	v_cvt_pk_bf16_f32 v42, v42, v183
	global_store_short v5, v42, s[54:55]
	s_add_u32 s54, s54, 0x40000
	s_addc_u32 s55, s55, 0
	v_cndmask_b32_e64 v43, 0, v43, s[40:41]
	v_cndmask_b32_e64 v59, 0, v59, s[42:43]
	v_cndmask_b32_e64 v75, 0, v75, s[44:45]
	v_add_f32_e32 v43, v43, v59
	v_add_f32_e32 v43, v43, v75
	v_cvt_pk_bf16_f32 v43, v43, v183
	global_store_short v5, v43, s[54:55]
	s_add_u32 s54, s54, 0x40000
	s_addc_u32 s55, s55, 0
	v_cndmask_b32_e64 v44, 0, v44, s[40:41]
	v_cndmask_b32_e64 v60, 0, v60, s[42:43]
	v_cndmask_b32_e64 v76, 0, v76, s[44:45]
	v_add_f32_e32 v44, v44, v60
	v_add_f32_e32 v44, v44, v76
	v_cvt_pk_bf16_f32 v44, v44, v183
	global_store_short v5, v44, s[54:55]
	s_add_u32 s54, s54, 0x40000
	s_addc_u32 s55, s55, 0
	v_cndmask_b32_e64 v45, 0, v45, s[40:41]
	v_cndmask_b32_e64 v61, 0, v61, s[42:43]
	v_cndmask_b32_e64 v77, 0, v77, s[44:45]
	v_add_f32_e32 v45, v45, v61
	v_add_f32_e32 v45, v45, v77
	v_cvt_pk_bf16_f32 v45, v45, v183
	global_store_short v5, v45, s[54:55]
	s_add_u32 s54, s54, 0x40000
	s_addc_u32 s55, s55, 0
	v_cndmask_b32_e64 v46, 0, v46, s[40:41]
	v_cndmask_b32_e64 v62, 0, v62, s[42:43]
	v_cndmask_b32_e64 v78, 0, v78, s[44:45]
	v_add_f32_e32 v46, v46, v62
	v_add_f32_e32 v46, v46, v78
	v_cvt_pk_bf16_f32 v46, v46, v183
	global_store_short v5, v46, s[54:55]
	s_add_u32 s54, s54, 0x40000
	s_addc_u32 s55, s55, 0
	v_cndmask_b32_e64 v47, 0, v47, s[40:41]
	v_cndmask_b32_e64 v63, 0, v63, s[42:43]
	v_cndmask_b32_e64 v79, 0, v79, s[44:45]
	v_add_f32_e32 v47, v47, v63
	v_add_f32_e32 v47, v47, v79
	v_cvt_pk_bf16_f32 v47, v47, v183
	global_store_short v5, v47, s[54:55]
	s_add_u32 s54, s54, 0x40000
	s_addc_u32 s55, s55, 0
	global_load_dword v32, v3, s[48:49]
	global_load_dword v48, v4, s[48:49]
	global_load_dword v64, v183, s[50:51] offset:1024
	s_add_u32 s48, s48, 0x8000
	s_addc_u32 s49, s49, 0
	global_load_dword v33, v3, s[48:49]
	global_load_dword v49, v4, s[48:49]
	global_load_dword v65, v183, s[50:51] offset:1088
	s_add_u32 s48, s48, 0x8000
	s_addc_u32 s49, s49, 0
	global_load_dword v34, v3, s[48:49]
	global_load_dword v50, v4, s[48:49]
	global_load_dword v66, v183, s[50:51] offset:1152
	s_add_u32 s48, s48, 0x8000
	s_addc_u32 s49, s49, 0
	global_load_dword v35, v3, s[48:49]
	global_load_dword v51, v4, s[48:49]
	global_load_dword v67, v183, s[50:51] offset:1216
	s_add_u32 s48, s48, 0x8000
	s_addc_u32 s49, s49, 0
	global_load_dword v36, v3, s[48:49]
	global_load_dword v52, v4, s[48:49]
	global_load_dword v68, v183, s[50:51] offset:1280
	s_add_u32 s48, s48, 0x8000
	s_addc_u32 s49, s49, 0
	global_load_dword v37, v3, s[48:49]
	global_load_dword v53, v4, s[48:49]
	global_load_dword v69, v183, s[50:51] offset:1344
	s_add_u32 s48, s48, 0x8000
	s_addc_u32 s49, s49, 0
	global_load_dword v38, v3, s[48:49]
	global_load_dword v54, v4, s[48:49]
	global_load_dword v70, v183, s[50:51] offset:1408
	s_add_u32 s48, s48, 0x8000
	s_addc_u32 s49, s49, 0
	global_load_dword v39, v3, s[48:49]
	global_load_dword v55, v4, s[48:49]
	global_load_dword v71, v183, s[50:51] offset:1472
	s_add_u32 s48, s48, 0x8000
	s_addc_u32 s49, s49, 0
	global_load_dword v40, v3, s[48:49]
	global_load_dword v56, v4, s[48:49]
	global_load_dword v72, v183, s[50:51] offset:1536
	s_add_u32 s48, s48, 0x8000
	s_addc_u32 s49, s49, 0
	global_load_dword v41, v3, s[48:49]
	global_load_dword v57, v4, s[48:49]
	global_load_dword v73, v183, s[50:51] offset:1600
	s_add_u32 s48, s48, 0x8000
	s_addc_u32 s49, s49, 0
	global_load_dword v42, v3, s[48:49]
	global_load_dword v58, v4, s[48:49]
	global_load_dword v74, v183, s[50:51] offset:1664
	s_add_u32 s48, s48, 0x8000
	s_addc_u32 s49, s49, 0
	global_load_dword v43, v3, s[48:49]
	global_load_dword v59, v4, s[48:49]
	global_load_dword v75, v183, s[50:51] offset:1728
	s_add_u32 s48, s48, 0x8000
	s_addc_u32 s49, s49, 0
	global_load_dword v44, v3, s[48:49]
	global_load_dword v60, v4, s[48:49]
	global_load_dword v76, v183, s[50:51] offset:1792
	s_add_u32 s48, s48, 0x8000
	s_addc_u32 s49, s49, 0
	global_load_dword v45, v3, s[48:49]
	global_load_dword v61, v4, s[48:49]
	global_load_dword v77, v183, s[50:51] offset:1856
	s_add_u32 s48, s48, 0x8000
	s_addc_u32 s49, s49, 0
	global_load_dword v46, v3, s[48:49]
	global_load_dword v62, v4, s[48:49]
	global_load_dword v78, v183, s[50:51] offset:1920
	s_add_u32 s48, s48, 0x8000
	s_addc_u32 s49, s49, 0
	global_load_dword v47, v3, s[48:49]
	global_load_dword v63, v4, s[48:49]
	global_load_dword v79, v183, s[50:51] offset:1984
	s_add_u32 s48, s48, 0x8000
	s_addc_u32 s49, s49, 0
	s_waitcnt vmcnt(0)
; __device__ __forceinline__ bf16_t f2bf(float f) { return (bf16_t)(cvt_pk_bf16(f, 0.f) & 0xffffu); }
; __device__ __forceinline__ void s5_assemble_w(const int TID, const int BID, const Params& p, int l) {
;     ...
;         if (k < 256) { const int s = k >> 4, cp = k & 15; val = 0.f;
;             const int jf = s <= t ? t - s : 0, jb = s >= t ? s - t : 0;
;             const float kf = kmat[((((size_t)g * 2 + 0) * 16 + jf) * 16 + c) * 16 + cp], kb = kmat[((((size_t)g * 2 + 1) * 16 + jb) * 16 + c) * 16 + cp], dsk = p.in[12][l * 512 + g * 16 + c];
;             val = (s <= t ? kf : 0.f) + (s >= t ? kb : 0.f) + ((s == t && c == cp) ? dsk : 0.f);
;         } else { const int kk = k - 256, d = kk >> 7, ri = (kk >> 6) & 1, n = kk & 63, j = d == 0 ? t + 1 : 16 - t;
;             const float cr = cre[(((size_t)(l * 2 + d) * 32 + g) * 16 + c) * 64 + n], ci = cim[(((size_t)(l * 2 + d) * 32 + g) * 16 + c) * 64 + n];
;             const f32x2 pv = pw[((size_t)(g * 2 + d) * 17 + j) * 64 + n];
;             val = ri == 0 ? cr * pv.x - ci * pv.y : -(cr * pv.y + ci * pv.x); }
;         wmat[idx] = f2bf(val);
	v_cndmask_b32_e64 v32, 0, v32, s[40:41]
	v_cndmask_b32_e64 v48, 0, v48, s[42:43]
	v_cndmask_b32_e64 v64, 0, v64, s[44:45]
	v_add_f32_e32 v32, v32, v48
	v_add_f32_e32 v32, v32, v64
	v_cvt_pk_bf16_f32 v32, v32, v183
	global_store_short v5, v32, s[54:55]
	s_add_u32 s54, s54, 0x40000
	s_addc_u32 s55, s55, 0
	v_cndmask_b32_e64 v33, 0, v33, s[40:41]
	v_cndmask_b32_e64 v49, 0, v49, s[42:43]
	v_cndmask_b32_e64 v65, 0, v65, s[44:45]
	v_add_f32_e32 v33, v33, v49
	v_add_f32_e32 v33, v33, v65
	v_cvt_pk_bf16_f32 v33, v33, v183
	global_store_short v5, v33, s[54:55]
	s_add_u32 s54, s54, 0x40000
	s_addc_u32 s55, s55, 0
	v_cndmask_b32_e64 v34, 0, v34, s[40:41]
	v_cndmask_b32_e64 v50, 0, v50, s[42:43]
	v_cndmask_b32_e64 v66, 0, v66, s[44:45]
	v_add_f32_e32 v34, v34, v50
	v_add_f32_e32 v34, v34, v66
	v_cvt_pk_bf16_f32 v34, v34, v183
	global_store_short v5, v34, s[54:55]
	s_add_u32 s54, s54, 0x40000
	s_addc_u32 s55, s55, 0
	v_cndmask_b32_e64 v35, 0, v35, s[40:41]
	v_cndmask_b32_e64 v51, 0, v51, s[42:43]
	v_cndmask_b32_e64 v67, 0, v67, s[44:45]
	v_add_f32_e32 v35, v35, v51
	v_add_f32_e32 v35, v35, v67
	v_cvt_pk_bf16_f32 v35, v35, v183
	global_store_short v5, v35, s[54:55]
	s_add_u32 s54, s54, 0x40000
	s_addc_u32 s55, s55, 0
	v_cndmask_b32_e64 v36, 0, v36, s[40:41]
	v_cndmask_b32_e64 v52, 0, v52, s[42:43]
	v_cndmask_b32_e64 v68, 0, v68, s[44:45]
	v_add_f32_e32 v36, v36, v52
	v_add_f32_e32 v36, v36, v68
	v_cvt_pk_bf16_f32 v36, v36, v183
	global_store_short v5, v36, s[54:55]
	s_add_u32 s54, s54, 0x40000
	s_addc_u32 s55, s55, 0
	v_cndmask_b32_e64 v37, 0, v37, s[40:41]
	v_cndmask_b32_e64 v53, 0, v53, s[42:43]
	v_cndmask_b32_e64 v69, 0, v69, s[44:45]
	v_add_f32_e32 v37, v37, v53
	v_add_f32_e32 v37, v37, v69
	v_cvt_pk_bf16_f32 v37, v37, v183
	global_store_short v5, v37, s[54:55]
	s_add_u32 s54, s54, 0x40000
	s_addc_u32 s55, s55, 0
	v_cndmask_b32_e64 v38, 0, v38, s[40:41]
	v_cndmask_b32_e64 v54, 0, v54, s[42:43]
	v_cndmask_b32_e64 v70, 0, v70, s[44:45]
	v_add_f32_e32 v38, v38, v54
	v_add_f32_e32 v38, v38, v70
	v_cvt_pk_bf16_f32 v38, v38, v183
	global_store_short v5, v38, s[54:55]
	s_add_u32 s54, s54, 0x40000
	s_addc_u32 s55, s55, 0
	v_cndmask_b32_e64 v39, 0, v39, s[40:41]
	v_cndmask_b32_e64 v55, 0, v55, s[42:43]
	v_cndmask_b32_e64 v71, 0, v71, s[44:45]
	v_add_f32_e32 v39, v39, v55
	v_add_f32_e32 v39, v39, v71
	v_cvt_pk_bf16_f32 v39, v39, v183
	global_store_short v5, v39, s[54:55]
	s_add_u32 s54, s54, 0x40000
	s_addc_u32 s55, s55, 0
	v_cndmask_b32_e64 v40, 0, v40, s[40:41]
	v_cndmask_b32_e64 v56, 0, v56, s[42:43]
	v_cndmask_b32_e64 v72, 0, v72, s[44:45]
	v_add_f32_e32 v40, v40, v56
	v_add_f32_e32 v40, v40, v72
	v_cvt_pk_bf16_f32 v40, v40, v183
	global_store_short v5, v40, s[54:55]
	s_add_u32 s54, s54, 0x40000
	s_addc_u32 s55, s55, 0
	v_cndmask_b32_e64 v41, 0, v41, s[40:41]
	v_cndmask_b32_e64 v57, 0, v57, s[42:43]
	v_cndmask_b32_e64 v73, 0, v73, s[44:45]
	v_add_f32_e32 v41, v41, v57
	v_add_f32_e32 v41, v41, v73
	v_cvt_pk_bf16_f32 v41, v41, v183
	global_store_short v5, v41, s[54:55]
	s_add_u32 s54, s54, 0x40000
	s_addc_u32 s55, s55, 0
	v_cndmask_b32_e64 v42, 0, v42, s[40:41]
	v_cndmask_b32_e64 v58, 0, v58, s[42:43]
	v_cndmask_b32_e64 v74, 0, v74, s[44:45]
	v_add_f32_e32 v42, v42, v58
	v_add_f32_e32 v42, v42, v74
	v_cvt_pk_bf16_f32 v42, v42, v183
	global_store_short v5, v42, s[54:55]
	s_add_u32 s54, s54, 0x40000
	s_addc_u32 s55, s55, 0
	v_cndmask_b32_e64 v43, 0, v43, s[40:41]
	v_cndmask_b32_e64 v59, 0, v59, s[42:43]
	v_cndmask_b32_e64 v75, 0, v75, s[44:45]
	v_add_f32_e32 v43, v43, v59
	v_add_f32_e32 v43, v43, v75
	v_cvt_pk_bf16_f32 v43, v43, v183
	global_store_short v5, v43, s[54:55]
	s_add_u32 s54, s54, 0x40000
	s_addc_u32 s55, s55, 0
	v_cndmask_b32_e64 v44, 0, v44, s[40:41]
	v_cndmask_b32_e64 v60, 0, v60, s[42:43]
	v_cndmask_b32_e64 v76, 0, v76, s[44:45]
	v_add_f32_e32 v44, v44, v60
	v_add_f32_e32 v44, v44, v76
	v_cvt_pk_bf16_f32 v44, v44, v183
	global_store_short v5, v44, s[54:55]
	s_add_u32 s54, s54, 0x40000
	s_addc_u32 s55, s55, 0
	v_cndmask_b32_e64 v45, 0, v45, s[40:41]
	v_cndmask_b32_e64 v61, 0, v61, s[42:43]
	v_cndmask_b32_e64 v77, 0, v77, s[44:45]
	v_add_f32_e32 v45, v45, v61
	v_add_f32_e32 v45, v45, v77
	v_cvt_pk_bf16_f32 v45, v45, v183
	global_store_short v5, v45, s[54:55]
	s_add_u32 s54, s54, 0x40000
	s_addc_u32 s55, s55, 0
	v_cndmask_b32_e64 v46, 0, v46, s[40:41]
	v_cndmask_b32_e64 v62, 0, v62, s[42:43]
	v_cndmask_b32_e64 v78, 0, v78, s[44:45]
	v_add_f32_e32 v46, v46, v62
	v_add_f32_e32 v46, v46, v78
	v_cvt_pk_bf16_f32 v46, v46, v183
	global_store_short v5, v46, s[54:55]
	s_add_u32 s54, s54, 0x40000
	s_addc_u32 s55, s55, 0
	v_cndmask_b32_e64 v47, 0, v47, s[40:41]
	v_cndmask_b32_e64 v63, 0, v63, s[42:43]
	v_cndmask_b32_e64 v79, 0, v79, s[44:45]
	v_add_f32_e32 v47, v47, v63
	v_add_f32_e32 v47, v47, v79
	v_cvt_pk_bf16_f32 v47, v47, v183
	global_store_short v5, v47, s[54:55]
	s_add_u32 s54, s54, 0x40000
	s_addc_u32 s55, s55, 0
	s_branch .LBB0_1022
